# G6 K-loop: next K-step LDS fragment reads placed one per MFMA gap (register double buffer), same as G5 loop
# baseline (speedup 1.0000x reference)
.LBB0_230:
	s_or_b64 exec, exec, s[6:7]
	v_add_u32_e32 v133, v131, v171
	v_add_u32_e32 v230, v130, v171
	s_setprio 1
	s_waitcnt lgkmcnt(0)
	v_mfma_f32_32x32x16_bf16 v[112:127], v[190:193], v[206:209], v[112:127]
	ds_read_b128 v[214:217], v133
	v_mfma_f32_32x32x16_bf16 v[96:111], v[190:193], v[210:213], v[96:111]
	ds_read_b128 v[218:221], v133 offset:4096
	v_mfma_f32_32x32x16_bf16 v[80:95], v[194:197], v[206:209], v[80:95]
	ds_read_b128 v[234:237], v133 offset:8192
	v_mfma_f32_32x32x16_bf16 v[64:79], v[194:197], v[210:213], v[64:79]
	ds_read_b128 v[238:241], v133 offset:12288
	v_mfma_f32_32x32x16_bf16 v[48:63], v[198:201], v[206:209], v[48:63]
	ds_read_b128 v[242:245], v230 offset:32768
	v_mfma_f32_32x32x16_bf16 v[32:47], v[198:201], v[210:213], v[32:47]
	ds_read_b128 v[246:249], v230 offset:36864
	v_mfma_f32_32x32x16_bf16 v[16:31], v[202:205], v[206:209], v[16:31]
	v_mfma_f32_32x32x16_bf16 v[0:15], v[202:205], v[210:213], v[0:15]
	s_setprio 0
	s_setprio 1
	s_waitcnt lgkmcnt(0)
	v_mfma_f32_32x32x16_bf16 v[112:127], v[214:217], v[242:245], v[112:127]
	v_mfma_f32_32x32x16_bf16 v[96:111], v[214:217], v[246:249], v[96:111]
	v_mfma_f32_32x32x16_bf16 v[80:95], v[218:221], v[242:245], v[80:95]
	v_mfma_f32_32x32x16_bf16 v[64:79], v[218:221], v[246:249], v[64:79]
	v_mfma_f32_32x32x16_bf16 v[48:63], v[234:237], v[242:245], v[48:63]
	v_mfma_f32_32x32x16_bf16 v[32:47], v[234:237], v[246:249], v[32:47]
	v_mfma_f32_32x32x16_bf16 v[16:31], v[238:241], v[242:245], v[16:31]
	v_mfma_f32_32x32x16_bf16 v[0:15], v[238:241], v[246:249], v[0:15]
	s_setprio 0
	s_xor_b32 s6, s9, 1
	s_waitcnt vmcnt(0)
	s_add_u32 s4, s4, 0x80
	s_addc_u32 s5, s5, 0
	s_cmpk_lg_i32 s4, 0x1f80
	s_waitcnt vmcnt(0)
	s_barrier
	s_cbranch_scc1 .LBB0_226
	v_add_u32_e32 v147, s8, v128
	v_cmp_lt_i32_e64 s[0:1], 23, v147
	s_xor_b64 s[4:5], vcc, -1
	s_nor_b64 s[4:5], s[4:5], s[0:1]
	v_cndmask_b32_e64 v128, v147, v128, s[0:1]
	v_ashrrev_i32_e32 v130, 31, v128
	v_lshrrev_b32_e32 v130, 30, v130
	v_add_u32_e32 v130, v128, v130
	v_lshrrev_b32_e32 v131, 2, v130
	v_and_b32_e32 v130, 0xfffffc, v130
	v_sub_u32_e32 v130, v128, v130
	v_lshlrev_b32_e32 v128, 4, v132
	v_and_b32_e32 v128, 0x70, v128
	v_add_lshl_u32 v146, v131, v166, 8
	v_lshl_add_u64 v[136:137], s[38:39], 0, v[128:129]
	v_lshl_add_u64 v[134:135], s[40:41], 0, v[128:129]
	v_lshlrev_b32_e32 v148, 8, v130
	s_and_saveexec_b64 s[14:15], s[4:5]
	s_xor_b64 s[4:5], exec, s[14:15]
	s_cbranch_execz .LBB0_233
	s_lshl_b32 s7, s6, 16
	s_xor_b32 s13, s7, 0x10000
	v_add_u32_e32 v130, v146, v188
	s_add_i32 s13, s13, 0
	v_ashrrev_i32_e32 v131, 31, v130
	v_add_u32_e32 v132, v187, v146
	v_add_u32_e32 v128, s13, v180
	v_lshlrev_b64 v[130:131], 13, v[130:131]
	v_ashrrev_i32_e32 v133, 31, v132
	v_readfirstlane_b32 s14, v128
	v_add_u32_e32 v142, s13, v179
	v_lshl_add_u64 v[130:131], v[136:137], 0, v[130:131]
	v_lshlrev_b64 v[132:133], 13, v[132:133]
	s_mov_b32 m0, s14
	v_readfirstlane_b32 s14, v142
	v_lshl_add_u64 v[132:133], v[136:137], 0, v[132:133]
	v_add_u32_e32 v138, v186, v146
	global_load_lds_dwordx4 v[130:131], off
	s_mov_b32 m0, s14
	v_ashrrev_i32_e32 v139, 31, v138
	v_add_u32_e32 v140, v185, v146
	global_load_lds_dwordx4 v[132:133], off
	v_add_u32_e32 v132, s13, v178
	v_lshlrev_b64 v[138:139], 13, v[138:139]
	v_ashrrev_i32_e32 v141, 31, v140
	v_readfirstlane_b32 s14, v132
	v_add_u32_e32 v133, s13, v177
	v_add_u32_e32 v130, v148, v188
	v_lshl_add_u64 v[138:139], v[136:137], 0, v[138:139]
	v_lshlrev_b64 v[140:141], 13, v[140:141]
	s_mov_b32 m0, s14
	v_readfirstlane_b32 s13, v133
	v_ashrrev_i32_e32 v131, 31, v130
	v_add_u32_e32 v128, 0x8000, v128
	v_lshl_add_u64 v[140:141], v[136:137], 0, v[140:141]
	global_load_lds_dwordx4 v[138:139], off
	s_mov_b32 m0, s13
	v_lshlrev_b64 v[130:131], 13, v[130:131]
	v_readfirstlane_b32 s13, v128
	global_load_lds_dwordx4 v[140:141], off
	v_lshl_add_u64 v[130:131], v[134:135], 0, v[130:131]
	s_mov_b32 m0, s13
	v_add_u32_e32 v128, 0x8000, v142
	global_load_lds_dwordx4 v[130:131], off
	v_add_u32_e32 v130, v187, v148
	v_ashrrev_i32_e32 v131, 31, v130
	v_lshlrev_b64 v[130:131], 13, v[130:131]
	v_readfirstlane_b32 s13, v128
	v_lshl_add_u64 v[130:131], v[134:135], 0, v[130:131]
	s_mov_b32 m0, s13
	v_add_u32_e32 v128, 0x8000, v132
	global_load_lds_dwordx4 v[130:131], off
	v_add_u32_e32 v130, v186, v148
	v_ashrrev_i32_e32 v131, 31, v130
	v_lshlrev_b64 v[130:131], 13, v[130:131]
	v_readfirstlane_b32 s13, v128
	v_lshl_add_u64 v[130:131], v[134:135], 0, v[130:131]
	s_mov_b32 m0, s13
	v_add_u32_e32 v128, 0x8000, v133
	global_load_lds_dwordx4 v[130:131], off
	v_add_u32_e32 v130, v185, v148
	v_ashrrev_i32_e32 v131, 31, v130
	v_lshlrev_b64 v[130:131], 13, v[130:131]
	v_readfirstlane_b32 s13, v128
	v_lshl_add_u64 v[130:131], v[134:135], 0, v[130:131]
	s_mov_b32 m0, s13
	s_nop 0
	global_load_lds_dwordx4 v[130:131], off
